# k34: static s_setprio 2 for the latency-critical scan roles (state chain, inverse, gram) over the throughput E roles sharing their SIMDs
# baseline (speedup 1.0000x reference)
.LBB0_801:
	s_or_b64 exec, exec, s[4:5]
	s_nop 2
	v_lshrrev_b32_e32 v0, 2, v148
	v_lshlrev_b32_e32 v2, 5, v148
	v_lshlrev_b32_e32 v1, 7, v0
	s_add_i32 s4, 0, 0x17c00
	v_and_b32_e32 v2, 0x60, v2
	v_add3_u32 v24, s4, v1, v2
	s_lshl_b64 s[4:5], s[0:1], 24
	v_lshl_or_b32 v0, v0, 11, s4
	s_and_b32 s4, s43, 0x780
	v_lshlrev_b32_e32 v1, 4, v42
	s_waitcnt lgkmcnt(0)
	s_barrier
	v_or3_b32 v0, v0, s4, v1
	v_mov_b32_e32 v1, s5
	v_lshl_add_u64 v[0:1], s[92:93], 0, v[0:1]
	s_mov_b64 s[4:5], 0x27d00040
	s_mov_b32 s33, 7
	v_lshl_add_u64 v[16:17], v[0:1], 0, s[4:5]
	s_movk_i32 s40, 0x4000
	v_lshlrev_b32_e32 v23, 1, v23
	s_mov_b32 s41, 0x5040100
	v_mov_b32_e32 v25, 0
	s_setprio 2
	s_branch .LBB0_804

.LBB0_812:
	s_and_b64 vcc, exec, s[46:47]
	s_cbranch_vccz .LBB0_841
	v_and_b32_e32 v0, 31, v128
	v_lshrrev_b32_e32 v1, 5, v148
	s_cmp_lt_u32 s61, 64
	v_mul_u32_u24_e32 v76, 0x90, v0
	v_lshlrev_b32_e32 v77, 3, v1
	v_mul_u32_u24_e32 v78, 24, v0
	v_and_b32_e32 v79, 32, v128
	v_lshlrev_b32_e32 v81, 9, v1
	s_mov_b64 s[4:5], -1
	v_lshlrev_b32_e32 v80, 5, v0
	v_lshlrev_b32_e32 v82, 2, v0
	s_cbranch_scc1 .LBB0_831
	s_add_i32 s4, 0, 0x17c00
	s_lshl_b32 s12, s42, 6
	s_lshl_b32 s10, s42, 4
	v_add3_u32 v83, s4, v81, v82
	s_lshl_b64 s[4:5], s[0:1], 21
	v_lshlrev_b32_e32 v0, 4, v148
	v_mov_b32_e32 v8, 0
	s_add_u32 s4, s92, s4
	v_and_b32_e32 v2, 48, v0
	v_lshlrev_b32_e32 v0, 8, v148
	v_mov_b32_e32 v1, v8
	s_addc_u32 s5, s93, s5
	v_lshl_add_u64 v[68:69], s[4:5], 0, v[0:1]
	s_lshl_b64 s[4:5], s[0:1], 23
	v_and_b32_e32 v1, 0x3c00, v0
	v_or_b32_e32 v1, s4, v1
	v_or3_b32 v2, v1, s12, v2
	s_lshl_b64 s[0:1], s[0:1], 24
	v_and_b32_e32 v0, 0x3800, v0
	v_and_b32_e32 v1, 7, v128
	v_mov_b32_e32 v3, s5
	v_or_b32_e32 v0, s0, v0
	s_lshl_b32 s0, s42, 7
	v_lshlrev_b32_e32 v1, 4, v1
	v_readlane_b32 s12, v254, 0
	v_lshl_add_u64 v[2:3], s[92:93], 0, v[2:3]
	s_mov_b64 s[4:5], 0x17b10000
	v_or3_b32 v0, v0, s0, v1
	v_mov_b32_e32 v1, s1
	v_readlane_b32 s18, v254, 6
	v_readlane_b32 s19, v254, 7
	v_mov_b32_e32 v14, v8
	v_mov_b32_e32 v15, v8
	v_lshl_add_u64 v[70:71], v[2:3], 0, s[4:5]
	v_lshl_add_u64 v[72:73], s[92:93], 0, v[0:1]
	v_readlane_b32 s13, v254, 1
	v_readlane_b32 s14, v254, 2
	v_readlane_b32 s15, v254, 3
	v_readlane_b32 s16, v254, 4
	v_readlane_b32 s17, v254, 5
	v_lshl_add_u64 v[74:75], s[18:19], 0, v[0:1]
	v_mov_b32_e32 v0, v8
	v_mov_b32_e32 v1, v8
	v_mov_b32_e32 v2, v8
	v_mov_b32_e32 v3, v8
	v_mov_b32_e32 v4, v8
	v_mov_b32_e32 v5, v8
	v_mov_b32_e32 v6, v8
	v_mov_b32_e32 v7, v8
	v_mov_b32_e32 v9, v8
	v_mov_b32_e32 v10, v8
	v_mov_b32_e32 v11, v8
	v_mov_b32_e32 v12, v8
	v_mov_b32_e32 v13, v8
	v_mov_b64_e32 v[30:31], v[14:15]
	v_mov_b64_e32 v[46:47], v[14:15]
	v_cmp_gt_u32_e64 s[6:7], 32, v148
	s_mov_b32 s33, 4
	v_cmp_gt_u32_e64 s[8:9], 16, v148
	s_mov_b32 s11, 0
	s_mov_b64 s[0:1], 0x2204000
	s_mov_b64 s[12:13], 0
	s_mov_b64 s[14:15], 0x37f20000
	s_mov_b64 s[16:17], 0x37f24000
	s_mov_b64 s[18:19], 0x20000
	s_mov_b64 s[20:21], 0x24000
	s_mov_b64 s[22:23], 0x8020000
	s_mov_b64 s[24:25], 0x8024000
	s_mov_b64 s[26:27], 0xfa20000
	s_mov_b64 s[28:29], 0xfa24000
	s_mov_b64 s[30:31], 0x2000
	s_mov_b64 s[34:35], 0x4000
	v_mov_b64_e32 v[28:29], v[12:13]
	v_mov_b64_e32 v[26:27], v[10:11]
	v_mov_b64_e32 v[24:25], v[8:9]
	v_mov_b64_e32 v[22:23], v[6:7]
	v_mov_b64_e32 v[20:21], v[4:5]
	v_mov_b64_e32 v[18:19], v[2:3]
	v_mov_b64_e32 v[16:17], v[0:1]
	v_mov_b64_e32 v[44:45], v[12:13]
	v_mov_b64_e32 v[42:43], v[10:11]
	v_mov_b64_e32 v[40:41], v[8:9]
	v_mov_b64_e32 v[38:39], v[6:7]
	v_mov_b64_e32 v[36:37], v[4:5]
	v_mov_b64_e32 v[34:35], v[2:3]
	v_mov_b64_e32 v[32:33], v[0:1]
	v_readfirstlane_b32 s64, v72
	v_readfirstlane_b32 s65, v73
	v_readfirstlane_b32 s66, v74
	v_readfirstlane_b32 s67, v75
	v_readfirstlane_b32 s68, v70
	v_readfirstlane_b32 s69, v71
	v_readfirstlane_b32 s70, v68
	v_readfirstlane_b32 s71, v69
	s_nop 1
	v_subrev_u32_e32 v102, s64, v72
	v_subrev_u32_e32 v103, s66, v74
	v_subrev_u32_e32 v104, s68, v70
	v_subrev_u32_e32 v105, s70, v68
	s_mov_b32 s78, 0xa400
	s_setprio 2
	s_branch .LBB0_817

.LBB0_831:
	s_and_b64 vcc, exec, s[4:5]
	s_cbranch_vccz .LBB0_840
	v_mov_b32_e32 v8, 0
	v_mov_b32_e32 v14, v8
	v_mov_b32_e32 v15, v8
	s_add_i32 s0, 0, 0x17c00
	v_mov_b32_e32 v0, v8
	v_mov_b32_e32 v1, v8
	v_mov_b32_e32 v2, v8
	v_mov_b32_e32 v3, v8
	v_mov_b32_e32 v4, v8
	v_mov_b32_e32 v5, v8
	v_mov_b32_e32 v6, v8
	v_mov_b32_e32 v7, v8
	v_mov_b32_e32 v9, v8
	v_mov_b32_e32 v10, v8
	v_mov_b32_e32 v11, v8
	v_mov_b32_e32 v12, v8
	v_mov_b32_e32 v13, v8
	v_mov_b64_e32 v[30:31], v[14:15]
	v_mov_b64_e32 v[46:47], v[14:15]
	v_add3_u32 v68, s0, v81, v82
	s_movk_i32 s6, 0xd000
	s_mov_b32 s7, -3
	v_mov_b64_e32 v[28:29], v[12:13]
	v_mov_b64_e32 v[26:27], v[10:11]
	v_mov_b64_e32 v[24:25], v[8:9]
	v_mov_b64_e32 v[22:23], v[6:7]
	v_mov_b64_e32 v[20:21], v[4:5]
	v_mov_b64_e32 v[18:19], v[2:3]
	v_mov_b64_e32 v[16:17], v[0:1]
	v_mov_b64_e32 v[44:45], v[12:13]
	v_mov_b64_e32 v[42:43], v[10:11]
	v_mov_b64_e32 v[40:41], v[8:9]
	v_mov_b64_e32 v[38:39], v[6:7]
	v_mov_b64_e32 v[36:37], v[4:5]
	v_mov_b64_e32 v[34:35], v[2:3]
	v_mov_b64_e32 v[32:33], v[0:1]
	s_setprio 2
	s_branch .LBB0_834

.LBB0_841:
	s_andn2_b64 vcc, exec, s[10:11]
	s_cbranch_vccnz .LBB0_849
	v_cmp_eq_u32_e64 s[0:1], 0, v148
	v_and_b32_e32 v16, 1, v128
	v_cmp_eq_u32_e64 s[6:7], 0, v16
	v_cndmask_b32_e64 v0, 0, 1.0, s[0:1]
	v_cmp_eq_u32_e64 s[0:1], 1, v148
	v_lshrrev_b32_e32 v16, 1, v128
	v_and_b32_e32 v18, 4, v16
	v_cndmask_b32_e64 v1, 0, 1.0, s[0:1]
	v_cmp_eq_u32_e64 s[0:1], 2, v148
	v_and_b32_e32 v17, 2, v128
	v_lshlrev_b32_e32 v16, 1, v148
	v_cndmask_b32_e64 v2, 0, 1.0, s[0:1]
	v_cmp_eq_u32_e64 s[0:1], 3, v148
	v_cmp_gt_u32_e32 vcc, 16, v148
	v_and_b32_e32 v16, 8, v16
	v_cndmask_b32_e64 v3, 0, 1.0, s[0:1]
	v_cmp_eq_u32_e64 s[0:1], 4, v148
	s_mov_b32 s4, -2
	v_lshlrev_b32_e32 v17, 1, v17
	v_cndmask_b32_e64 v4, 0, 1.0, s[0:1]
	v_cmp_eq_u32_e64 s[0:1], 5, v148
	v_lshlrev_b32_e32 v18, 1, v18
	s_nop 0
	v_cndmask_b32_e64 v5, 0, 1.0, s[0:1]
	v_cmp_eq_u32_e64 s[0:1], 6, v148
	s_nop 1
	v_cndmask_b32_e64 v6, 0, 1.0, s[0:1]
	v_cmp_eq_u32_e64 s[0:1], 7, v148
	s_nop 1
	v_cndmask_b32_e64 v7, 0, 1.0, s[0:1]
	v_cmp_eq_u32_e64 s[0:1], 8, v148
	s_nop 1
	v_cndmask_b32_e64 v8, 0, 1.0, s[0:1]
	v_cmp_eq_u32_e64 s[0:1], 9, v148
	s_nop 1
	v_cndmask_b32_e64 v9, 0, 1.0, s[0:1]
	v_cmp_eq_u32_e64 s[0:1], 10, v148
	s_nop 1
	v_cndmask_b32_e64 v10, 0, 1.0, s[0:1]
	v_cmp_eq_u32_e64 s[0:1], 11, v148
	s_nop 1
	v_cndmask_b32_e64 v11, 0, 1.0, s[0:1]
	v_cmp_eq_u32_e64 s[0:1], 12, v148
	s_nop 1
	v_cndmask_b32_e64 v12, 0, 1.0, s[0:1]
	v_cmp_eq_u32_e64 s[0:1], 13, v148
	s_nop 1
	v_cndmask_b32_e64 v13, 0, 1.0, s[0:1]
	v_cmp_eq_u32_e64 s[0:1], 14, v148
	s_nop 1
	v_cndmask_b32_e64 v14, 0, 1.0, s[0:1]
	v_cmp_eq_u32_e64 s[0:1], 15, v148
	s_nop 1
	v_cndmask_b32_e64 v15, 0, 1.0, s[0:1]
	s_setprio 2
	s_branch .LBB0_845

.LBB0_850:
	s_setprio 0
	s_waitcnt vmcnt(0)
	s_waitcnt vmcnt(0)
	s_barrier
	s_and_saveexec_b64 s[0:1], s[56:57]
	v_readlane_b32 s96, v254, 12
	v_readlane_b32 s97, v254, 13
	v_readlane_b32 s53, v254, 11
	s_cbranch_execz .LBB0_902
	s_add_i32 s4, 0, 0x27fc0
	v_mov_b32_e32 v0, s4
	s_waitcnt vmcnt(0) expcnt(0) lgkmcnt(0)
	ds_read_b32 v2, v0
	s_add_i32 s4, 0, 0x27fc4
	v_mov_b32_e32 v0, s4
	ds_read_b32 v0, v0
	s_waitcnt lgkmcnt(1)
	v_cmp_ne_u32_e32 vcc, 0, v2
	s_cbranch_vccnz .LBB0_866
	s_add_u32 s6, s92, 0x1200
	s_addc_u32 s7, s93, 0
	s_add_u32 s8, s92, 0x1400
	s_addc_u32 s9, s93, 0
	s_add_u32 s10, s92, 0x1500
	s_addc_u32 s11, s93, 0
	s_add_u32 s12, s92, 0x1600
	s_addc_u32 s13, s93, 0
	s_add_u32 s14, s92, 0x1700
	s_addc_u32 s15, s93, 0
	s_add_u32 s16, s92, 0x1800
	s_addc_u32 s17, s93, 0
	s_add_u32 s18, s92, 0x1900
	s_addc_u32 s19, s93, 0
	s_add_u32 s20, s92, 0x1a00
	s_addc_u32 s21, s93, 0
	s_add_u32 s22, s92, 0x1b00
	s_addc_u32 s23, s93, 0
	s_add_u32 s24, s92, 0x1c00
	s_addc_u32 s25, s93, 0
	s_add_u32 s26, s92, 0x1d00
	s_addc_u32 s27, s93, 0
	s_add_u32 s28, s92, 0x1e00
	s_addc_u32 s29, s93, 0
	s_add_u32 s30, s92, 0x1f00
	v_readlane_b32 s4, v254, 10
	s_addc_u32 s31, s93, 0
	s_mul_i32 s33, s95, s4
	s_add_u32 s4, s92, 0x2000
	s_addc_u32 s5, s93, 0
	s_add_u32 s34, s92, 0x2100
	s_addc_u32 s35, s93, 0
	s_add_u32 s36, s92, 0x2200
	s_addc_u32 s37, s93, 0
	s_add_u32 s38, s92, 0x2300
	s_mul_i32 s33, s33, s94
	s_addc_u32 s39, s93, 0
	s_mov_b32 s44, 1
	v_mov_b32_e32 v16, 0
	s_branch .LBB0_854
